# norm phases: the 22 K-split partial tiles of each sample row are loaded 7 tiles per wait (was 2 loads per wait, 44 serial round trips) and summed in f32 trees
# speedup vs baseline: 1.0054x; 1.0054x over previous
; template <bool FINAL>
; DI void norm_rows(const Params& p, const float* gain, int in_mode  , int npart  , int pool_j  , int gw, int NGW, int lane) {
;     ...
;     for (int row = gw; row < MA; row += NGW) {
;         const float* xr = (row < MP) ? (in_mode == 1 ? p.in[0] + (size_t)row * D : X + (size_t)row * D) : (in_mode ? p.in[1] + (size_t)(row - MP) * D : X + (size_t)row * D);
;         f32x4 v[4]; float s = 0.f;
; #pragma unroll
;         for (int j = 0; j < 4; ++j) v[j] = *(const f32x4*)(xr + 4 * lane + 256 * j);
;         if (row >= MP && npart > 0) {
;             const float* pp = (const float*)(p.ws + WS_PART) + (size_t)(row - MP) * D + 4 * lane;
;             int k = 0;
;             for (; k + 4 <= npart; k += 4) {
;                 f32x4 t[4][4];
; #pragma unroll
;                 for (int kk = 0; kk < 4; ++kk)
; #pragma unroll
;                     for (int j = 0; j < 4; ++j) t[kk][j] = *(const f32x4*)(pp + (size_t)(k + kk) * MS * D + 256 * j);
; #pragma unroll
;                 for (int j = 0; j < 4; ++j) v[j] += (t[0][j] + t[1][j]) + (t[2][j] + t[3][j]);
;             }
.LBB0_62:
	s_cmp_lt_i32 s0, 0x8000
	s_cselect_b64 s[4:5], -1, 0
	s_and_b64 vcc, s[4:5], exec
	s_cselect_b32 s5, s1, 0
	s_mov_b32 s4, s0
	s_lshl_b64 s[4:5], s[4:5], 12
	v_lshl_add_u64 v[28:29], v[48:49], 0, s[4:5]
	global_load_dwordx4 v[24:27], v[28:29], off
	global_load_dwordx4 v[20:23], v[28:29], off offset:1024
	global_load_dwordx4 v[16:19], v[28:29], off offset:2048
	s_nop 0
	global_load_dwordx4 v[28:31], v[28:29], off offset:3072
	s_cbranch_vccnz .LBB0_61
	s_add_i32 s8, s0, 0xffff8000
	s_lshl_b64 s[4:5], s[8:9], 12
	v_lshl_add_u64 v[32:33], v[50:51], 0, s[4:5]
	s_mov_b64 s[4:5], 0x200000
	global_load_dwordx4 v[104:107], v[32:33], off
	global_load_dwordx4 v[108:111], v[32:33], off offset:1024
	global_load_dwordx4 v[112:115], v[32:33], off offset:2048
	global_load_dwordx4 v[116:119], v[32:33], off offset:3072
	v_lshl_add_u64 v[32:33], v[32:33], 0, s[4:5]
	global_load_dwordx4 v[120:123], v[32:33], off
	global_load_dwordx4 v[124:127], v[32:33], off offset:1024
	global_load_dwordx4 v[128:131], v[32:33], off offset:2048
	global_load_dwordx4 v[132:135], v[32:33], off offset:3072
	v_lshl_add_u64 v[32:33], v[32:33], 0, s[4:5]
	global_load_dwordx4 v[136:139], v[32:33], off
	global_load_dwordx4 v[140:143], v[32:33], off offset:1024
	global_load_dwordx4 v[144:147], v[32:33], off offset:2048
	global_load_dwordx4 v[148:151], v[32:33], off offset:3072
	v_lshl_add_u64 v[32:33], v[32:33], 0, s[4:5]
	global_load_dwordx4 v[152:155], v[32:33], off
	global_load_dwordx4 v[156:159], v[32:33], off offset:1024
	global_load_dwordx4 v[160:163], v[32:33], off offset:2048
	global_load_dwordx4 v[164:167], v[32:33], off offset:3072
	v_lshl_add_u64 v[32:33], v[32:33], 0, s[4:5]
	global_load_dwordx4 v[168:171], v[32:33], off
	global_load_dwordx4 v[172:175], v[32:33], off offset:1024
	global_load_dwordx4 v[176:179], v[32:33], off offset:2048
	global_load_dwordx4 v[180:183], v[32:33], off offset:3072
	v_lshl_add_u64 v[32:33], v[32:33], 0, s[4:5]
	global_load_dwordx4 v[184:187], v[32:33], off
	global_load_dwordx4 v[188:191], v[32:33], off offset:1024
	global_load_dwordx4 v[192:195], v[32:33], off offset:2048
	global_load_dwordx4 v[196:199], v[32:33], off offset:3072
	v_lshl_add_u64 v[32:33], v[32:33], 0, s[4:5]
	global_load_dwordx4 v[200:203], v[32:33], off
	global_load_dwordx4 v[204:207], v[32:33], off offset:1024
	global_load_dwordx4 v[208:211], v[32:33], off offset:2048
	global_load_dwordx4 v[212:215], v[32:33], off offset:3072
	v_lshl_add_u64 v[32:33], v[32:33], 0, s[4:5]
	s_waitcnt vmcnt(0)
	v_pk_add_f32 v[104:105], v[104:105], v[120:121]
	v_pk_add_f32 v[106:107], v[106:107], v[122:123]
	v_pk_add_f32 v[136:137], v[136:137], v[152:153]
	v_pk_add_f32 v[138:139], v[138:139], v[154:155]
	v_pk_add_f32 v[168:169], v[168:169], v[184:185]
	v_pk_add_f32 v[170:171], v[170:171], v[186:187]
	v_pk_add_f32 v[168:169], v[168:169], v[200:201]
	v_pk_add_f32 v[170:171], v[170:171], v[202:203]
	v_pk_add_f32 v[104:105], v[104:105], v[136:137]
	v_pk_add_f32 v[106:107], v[106:107], v[138:139]
	v_pk_add_f32 v[104:105], v[104:105], v[168:169]
	v_pk_add_f32 v[106:107], v[106:107], v[170:171]
	v_pk_add_f32 v[24:25], v[24:25], v[104:105]
	v_pk_add_f32 v[26:27], v[26:27], v[106:107]
	v_pk_add_f32 v[108:109], v[108:109], v[124:125]
	v_pk_add_f32 v[110:111], v[110:111], v[126:127]
	v_pk_add_f32 v[140:141], v[140:141], v[156:157]
	v_pk_add_f32 v[142:143], v[142:143], v[158:159]
	v_pk_add_f32 v[172:173], v[172:173], v[188:189]
	v_pk_add_f32 v[174:175], v[174:175], v[190:191]
	v_pk_add_f32 v[172:173], v[172:173], v[204:205]
	v_pk_add_f32 v[174:175], v[174:175], v[206:207]
	v_pk_add_f32 v[108:109], v[108:109], v[140:141]
	v_pk_add_f32 v[110:111], v[110:111], v[142:143]
	v_pk_add_f32 v[108:109], v[108:109], v[172:173]
	v_pk_add_f32 v[110:111], v[110:111], v[174:175]
	v_pk_add_f32 v[20:21], v[20:21], v[108:109]
	v_pk_add_f32 v[22:23], v[22:23], v[110:111]
	v_pk_add_f32 v[112:113], v[112:113], v[128:129]
	v_pk_add_f32 v[114:115], v[114:115], v[130:131]
	v_pk_add_f32 v[144:145], v[144:145], v[160:161]
	v_pk_add_f32 v[146:147], v[146:147], v[162:163]
	v_pk_add_f32 v[176:177], v[176:177], v[192:193]
	v_pk_add_f32 v[178:179], v[178:179], v[194:195]
	v_pk_add_f32 v[176:177], v[176:177], v[208:209]
	v_pk_add_f32 v[178:179], v[178:179], v[210:211]
	v_pk_add_f32 v[112:113], v[112:113], v[144:145]
	v_pk_add_f32 v[114:115], v[114:115], v[146:147]
	v_pk_add_f32 v[112:113], v[112:113], v[176:177]
	v_pk_add_f32 v[114:115], v[114:115], v[178:179]
	v_pk_add_f32 v[16:17], v[16:17], v[112:113]
	v_pk_add_f32 v[18:19], v[18:19], v[114:115]
	v_pk_add_f32 v[116:117], v[116:117], v[132:133]
	v_pk_add_f32 v[118:119], v[118:119], v[134:135]
	v_pk_add_f32 v[148:149], v[148:149], v[164:165]
	v_pk_add_f32 v[150:151], v[150:151], v[166:167]
	v_pk_add_f32 v[180:181], v[180:181], v[196:197]
	v_pk_add_f32 v[182:183], v[182:183], v[198:199]
	v_pk_add_f32 v[180:181], v[180:181], v[212:213]
	v_pk_add_f32 v[182:183], v[182:183], v[214:215]
	v_pk_add_f32 v[116:117], v[116:117], v[148:149]
	v_pk_add_f32 v[118:119], v[118:119], v[150:151]
	v_pk_add_f32 v[116:117], v[116:117], v[180:181]
	v_pk_add_f32 v[118:119], v[118:119], v[182:183]
	v_pk_add_f32 v[28:29], v[28:29], v[116:117]
	v_pk_add_f32 v[30:31], v[30:31], v[118:119]
	global_load_dwordx4 v[104:107], v[32:33], off
	global_load_dwordx4 v[108:111], v[32:33], off offset:1024
	global_load_dwordx4 v[112:115], v[32:33], off offset:2048
	global_load_dwordx4 v[116:119], v[32:33], off offset:3072
	v_lshl_add_u64 v[32:33], v[32:33], 0, s[4:5]
	global_load_dwordx4 v[120:123], v[32:33], off
	global_load_dwordx4 v[124:127], v[32:33], off offset:1024
	global_load_dwordx4 v[128:131], v[32:33], off offset:2048
; template <bool FINAL>
; DI void norm_rows(const Params& p, const float* gain, int in_mode  , int npart  , int pool_j  , int gw, int NGW, int lane) {
;     ...
;         if (row >= MP && npart > 0) {
;             const float* pp = (const float*)(p.ws + WS_PART) + (size_t)(row - MP) * D + 4 * lane;
;             int k = 0;
;             for (; k + 4 <= npart; k += 4) {
;                 f32x4 t[4][4];
; #pragma unroll
;                 for (int kk = 0; kk < 4; ++kk)
; #pragma unroll
;                     for (int j = 0; j < 4; ++j) t[kk][j] = *(const f32x4*)(pp + (size_t)(k + kk) * MS * D + 256 * j);
; #pragma unroll
;                 for (int j = 0; j < 4; ++j) v[j] += (t[0][j] + t[1][j]) + (t[2][j] + t[3][j]);
;             }
	global_load_dwordx4 v[132:135], v[32:33], off offset:3072
	v_lshl_add_u64 v[32:33], v[32:33], 0, s[4:5]
	global_load_dwordx4 v[136:139], v[32:33], off
	global_load_dwordx4 v[140:143], v[32:33], off offset:1024
	global_load_dwordx4 v[144:147], v[32:33], off offset:2048
	global_load_dwordx4 v[148:151], v[32:33], off offset:3072
	v_lshl_add_u64 v[32:33], v[32:33], 0, s[4:5]
	global_load_dwordx4 v[152:155], v[32:33], off
	global_load_dwordx4 v[156:159], v[32:33], off offset:1024
	global_load_dwordx4 v[160:163], v[32:33], off offset:2048
	global_load_dwordx4 v[164:167], v[32:33], off offset:3072
	v_lshl_add_u64 v[32:33], v[32:33], 0, s[4:5]
	global_load_dwordx4 v[168:171], v[32:33], off
	global_load_dwordx4 v[172:175], v[32:33], off offset:1024
	global_load_dwordx4 v[176:179], v[32:33], off offset:2048
	global_load_dwordx4 v[180:183], v[32:33], off offset:3072
	v_lshl_add_u64 v[32:33], v[32:33], 0, s[4:5]
	global_load_dwordx4 v[184:187], v[32:33], off
	global_load_dwordx4 v[188:191], v[32:33], off offset:1024
	global_load_dwordx4 v[192:195], v[32:33], off offset:2048
	global_load_dwordx4 v[196:199], v[32:33], off offset:3072
	v_lshl_add_u64 v[32:33], v[32:33], 0, s[4:5]
	global_load_dwordx4 v[200:203], v[32:33], off
	global_load_dwordx4 v[204:207], v[32:33], off offset:1024
	global_load_dwordx4 v[208:211], v[32:33], off offset:2048
	global_load_dwordx4 v[212:215], v[32:33], off offset:3072
	v_lshl_add_u64 v[32:33], v[32:33], 0, s[4:5]
	s_waitcnt vmcnt(0)
	v_pk_add_f32 v[104:105], v[104:105], v[120:121]
	v_pk_add_f32 v[106:107], v[106:107], v[122:123]
	v_pk_add_f32 v[136:137], v[136:137], v[152:153]
	v_pk_add_f32 v[138:139], v[138:139], v[154:155]
	v_pk_add_f32 v[168:169], v[168:169], v[184:185]
	v_pk_add_f32 v[170:171], v[170:171], v[186:187]
	v_pk_add_f32 v[168:169], v[168:169], v[200:201]
	v_pk_add_f32 v[170:171], v[170:171], v[202:203]
	v_pk_add_f32 v[104:105], v[104:105], v[136:137]
	v_pk_add_f32 v[106:107], v[106:107], v[138:139]
	v_pk_add_f32 v[104:105], v[104:105], v[168:169]
	v_pk_add_f32 v[106:107], v[106:107], v[170:171]
	v_pk_add_f32 v[24:25], v[24:25], v[104:105]
	v_pk_add_f32 v[26:27], v[26:27], v[106:107]
	v_pk_add_f32 v[108:109], v[108:109], v[124:125]
	v_pk_add_f32 v[110:111], v[110:111], v[126:127]
	v_pk_add_f32 v[140:141], v[140:141], v[156:157]
	v_pk_add_f32 v[142:143], v[142:143], v[158:159]
	v_pk_add_f32 v[172:173], v[172:173], v[188:189]
	v_pk_add_f32 v[174:175], v[174:175], v[190:191]
	v_pk_add_f32 v[172:173], v[172:173], v[204:205]
	v_pk_add_f32 v[174:175], v[174:175], v[206:207]
	v_pk_add_f32 v[108:109], v[108:109], v[140:141]
	v_pk_add_f32 v[110:111], v[110:111], v[142:143]
	v_pk_add_f32 v[108:109], v[108:109], v[172:173]
	v_pk_add_f32 v[110:111], v[110:111], v[174:175]
	v_pk_add_f32 v[20:21], v[20:21], v[108:109]
	v_pk_add_f32 v[22:23], v[22:23], v[110:111]
	v_pk_add_f32 v[112:113], v[112:113], v[128:129]
	v_pk_add_f32 v[114:115], v[114:115], v[130:131]
	v_pk_add_f32 v[144:145], v[144:145], v[160:161]
	v_pk_add_f32 v[146:147], v[146:147], v[162:163]
	v_pk_add_f32 v[176:177], v[176:177], v[192:193]
	v_pk_add_f32 v[178:179], v[178:179], v[194:195]
	v_pk_add_f32 v[176:177], v[176:177], v[208:209]
	v_pk_add_f32 v[178:179], v[178:179], v[210:211]
	v_pk_add_f32 v[112:113], v[112:113], v[144:145]
	v_pk_add_f32 v[114:115], v[114:115], v[146:147]
	v_pk_add_f32 v[112:113], v[112:113], v[176:177]
	v_pk_add_f32 v[114:115], v[114:115], v[178:179]
	v_pk_add_f32 v[16:17], v[16:17], v[112:113]
	v_pk_add_f32 v[18:19], v[18:19], v[114:115]
	v_pk_add_f32 v[116:117], v[116:117], v[132:133]
	v_pk_add_f32 v[118:119], v[118:119], v[134:135]
	v_pk_add_f32 v[148:149], v[148:149], v[164:165]
	v_pk_add_f32 v[150:151], v[150:151], v[166:167]
	v_pk_add_f32 v[180:181], v[180:181], v[196:197]
	v_pk_add_f32 v[182:183], v[182:183], v[198:199]
	v_pk_add_f32 v[180:181], v[180:181], v[212:213]
	v_pk_add_f32 v[182:183], v[182:183], v[214:215]
	v_pk_add_f32 v[116:117], v[116:117], v[148:149]
	v_pk_add_f32 v[118:119], v[118:119], v[150:151]
	v_pk_add_f32 v[116:117], v[116:117], v[180:181]
	v_pk_add_f32 v[118:119], v[118:119], v[182:183]
	v_pk_add_f32 v[28:29], v[28:29], v[116:117]
	v_pk_add_f32 v[30:31], v[30:31], v[118:119]
	global_load_dwordx4 v[104:107], v[32:33], off
	global_load_dwordx4 v[108:111], v[32:33], off offset:1024
	global_load_dwordx4 v[112:115], v[32:33], off offset:2048
	global_load_dwordx4 v[116:119], v[32:33], off offset:3072
	v_lshl_add_u64 v[32:33], v[32:33], 0, s[4:5]
	global_load_dwordx4 v[120:123], v[32:33], off
	global_load_dwordx4 v[124:127], v[32:33], off offset:1024
	global_load_dwordx4 v[128:131], v[32:33], off offset:2048
	global_load_dwordx4 v[132:135], v[32:33], off offset:3072
	v_lshl_add_u64 v[32:33], v[32:33], 0, s[4:5]
	global_load_dwordx4 v[136:139], v[32:33], off
	global_load_dwordx4 v[140:143], v[32:33], off offset:1024
	global_load_dwordx4 v[144:147], v[32:33], off offset:2048
	global_load_dwordx4 v[148:151], v[32:33], off offset:3072
	v_lshl_add_u64 v[32:33], v[32:33], 0, s[4:5]
	global_load_dwordx4 v[152:155], v[32:33], off
	global_load_dwordx4 v[156:159], v[32:33], off offset:1024
	global_load_dwordx4 v[160:163], v[32:33], off offset:2048
	global_load_dwordx4 v[164:167], v[32:33], off offset:3072
	v_lshl_add_u64 v[32:33], v[32:33], 0, s[4:5]
	global_load_dwordx4 v[168:171], v[32:33], off
	global_load_dwordx4 v[172:175], v[32:33], off offset:1024
	global_load_dwordx4 v[176:179], v[32:33], off offset:2048
	global_load_dwordx4 v[180:183], v[32:33], off offset:3072
	v_lshl_add_u64 v[32:33], v[32:33], 0, s[4:5]
	global_load_dwordx4 v[184:187], v[32:33], off
	global_load_dwordx4 v[188:191], v[32:33], off offset:1024
	global_load_dwordx4 v[192:195], v[32:33], off offset:2048
	global_load_dwordx4 v[196:199], v[32:33], off offset:3072
	v_lshl_add_u64 v[32:33], v[32:33], 0, s[4:5]
	global_load_dwordx4 v[200:203], v[32:33], off
	global_load_dwordx4 v[204:207], v[32:33], off offset:1024
	global_load_dwordx4 v[208:211], v[32:33], off offset:2048
	global_load_dwordx4 v[212:215], v[32:33], off offset:3072
	v_lshl_add_u64 v[32:33], v[32:33], 0, s[4:5]
	s_waitcnt vmcnt(0)
; template <bool FINAL>
; DI void norm_rows(const Params& p, const float* gain, int in_mode  , int npart  , int pool_j  , int gw, int NGW, int lane) {
;     ...
;             for (; k + 4 <= npart; k += 4) {
;                 f32x4 t[4][4];
; #pragma unroll
;                 for (int kk = 0; kk < 4; ++kk)
; #pragma unroll
;                     for (int j = 0; j < 4; ++j) t[kk][j] = *(const f32x4*)(pp + (size_t)(k + kk) * MS * D + 256 * j);
; #pragma unroll
;                 for (int j = 0; j < 4; ++j) v[j] += (t[0][j] + t[1][j]) + (t[2][j] + t[3][j]);
;             }
	v_pk_add_f32 v[104:105], v[104:105], v[120:121]
	v_pk_add_f32 v[106:107], v[106:107], v[122:123]
	v_pk_add_f32 v[136:137], v[136:137], v[152:153]
	v_pk_add_f32 v[138:139], v[138:139], v[154:155]
	v_pk_add_f32 v[168:169], v[168:169], v[184:185]
	v_pk_add_f32 v[170:171], v[170:171], v[186:187]
	v_pk_add_f32 v[168:169], v[168:169], v[200:201]
	v_pk_add_f32 v[170:171], v[170:171], v[202:203]
	v_pk_add_f32 v[104:105], v[104:105], v[136:137]
	v_pk_add_f32 v[106:107], v[106:107], v[138:139]
	v_pk_add_f32 v[104:105], v[104:105], v[168:169]
	v_pk_add_f32 v[106:107], v[106:107], v[170:171]
	v_pk_add_f32 v[24:25], v[24:25], v[104:105]
	v_pk_add_f32 v[26:27], v[26:27], v[106:107]
	v_pk_add_f32 v[108:109], v[108:109], v[124:125]
	v_pk_add_f32 v[110:111], v[110:111], v[126:127]
	v_pk_add_f32 v[140:141], v[140:141], v[156:157]
	v_pk_add_f32 v[142:143], v[142:143], v[158:159]
	v_pk_add_f32 v[172:173], v[172:173], v[188:189]
	v_pk_add_f32 v[174:175], v[174:175], v[190:191]
	v_pk_add_f32 v[172:173], v[172:173], v[204:205]
	v_pk_add_f32 v[174:175], v[174:175], v[206:207]
	v_pk_add_f32 v[108:109], v[108:109], v[140:141]
	v_pk_add_f32 v[110:111], v[110:111], v[142:143]
	v_pk_add_f32 v[108:109], v[108:109], v[172:173]
	v_pk_add_f32 v[110:111], v[110:111], v[174:175]
	v_pk_add_f32 v[20:21], v[20:21], v[108:109]
	v_pk_add_f32 v[22:23], v[22:23], v[110:111]
	v_pk_add_f32 v[112:113], v[112:113], v[128:129]
	v_pk_add_f32 v[114:115], v[114:115], v[130:131]
	v_pk_add_f32 v[144:145], v[144:145], v[160:161]
	v_pk_add_f32 v[146:147], v[146:147], v[162:163]
	v_pk_add_f32 v[176:177], v[176:177], v[192:193]
	v_pk_add_f32 v[178:179], v[178:179], v[194:195]
	v_pk_add_f32 v[176:177], v[176:177], v[208:209]
	v_pk_add_f32 v[178:179], v[178:179], v[210:211]
	v_pk_add_f32 v[112:113], v[112:113], v[144:145]
	v_pk_add_f32 v[114:115], v[114:115], v[146:147]
	v_pk_add_f32 v[112:113], v[112:113], v[176:177]
	v_pk_add_f32 v[114:115], v[114:115], v[178:179]
	v_pk_add_f32 v[16:17], v[16:17], v[112:113]
	v_pk_add_f32 v[18:19], v[18:19], v[114:115]
	v_pk_add_f32 v[116:117], v[116:117], v[132:133]
	v_pk_add_f32 v[118:119], v[118:119], v[134:135]
	v_pk_add_f32 v[148:149], v[148:149], v[164:165]
	v_pk_add_f32 v[150:151], v[150:151], v[166:167]
	v_pk_add_f32 v[180:181], v[180:181], v[196:197]
	v_pk_add_f32 v[182:183], v[182:183], v[198:199]
	v_pk_add_f32 v[180:181], v[180:181], v[212:213]
	v_pk_add_f32 v[182:183], v[182:183], v[214:215]
	v_pk_add_f32 v[116:117], v[116:117], v[148:149]
	v_pk_add_f32 v[118:119], v[118:119], v[150:151]
	v_pk_add_f32 v[116:117], v[116:117], v[180:181]
	v_pk_add_f32 v[118:119], v[118:119], v[182:183]
	v_pk_add_f32 v[28:29], v[28:29], v[116:117]
	v_pk_add_f32 v[30:31], v[30:31], v[118:119]
	global_load_dwordx4 v[104:107], v[32:33], off
	global_load_dwordx4 v[108:111], v[32:33], off offset:1024
	global_load_dwordx4 v[112:115], v[32:33], off offset:2048
	global_load_dwordx4 v[116:119], v[32:33], off offset:3072
	v_lshl_add_u64 v[32:33], v[32:33], 0, s[4:5]
	s_waitcnt vmcnt(0)
	v_pk_add_f32 v[24:25], v[24:25], v[104:105]
	v_pk_add_f32 v[26:27], v[26:27], v[106:107]
	v_pk_add_f32 v[20:21], v[20:21], v[108:109]
	v_pk_add_f32 v[22:23], v[22:23], v[110:111]
	v_pk_add_f32 v[16:17], v[16:17], v[112:113]
	v_pk_add_f32 v[18:19], v[18:19], v[114:115]
	v_pk_add_f32 v[28:29], v[28:29], v[116:117]
	v_pk_add_f32 v[30:31], v[30:31], v[118:119]
	s_branch .LBB0_61

; template <bool FINAL>
; DI void norm_rows(const Params& p, const float* gain, int in_mode  , int npart  , int pool_j  , int gw, int NGW, int lane) {
;     ...
;         if (row >= MP && npart > 0) {
;             const float* pp = (const float*)(p.ws + WS_PART) + (size_t)(row - MP) * D + 4 * lane;
;             int k = 0;
;             for (; k + 4 <= npart; k += 4) {
;                 f32x4 t[4][4];
; #pragma unroll
;                 for (int kk = 0; kk < 4; ++kk)
; #pragma unroll
;                     for (int j = 0; j < 4; ++j) t[kk][j] = *(const f32x4*)(pp + (size_t)(k + kk) * MS * D + 256 * j);
; #pragma unroll
;                 for (int j = 0; j < 4; ++j) v[j] += (t[0][j] + t[1][j]) + (t[2][j] + t[3][j]);
;             }
.LBB0_1602:
	s_andn2_b64 vcc, exec, s[4:5]
	s_cbranch_vccnz .LBB0_1604
	s_add_i32 s8, s28, 0xffff8000
	s_lshl_b64 s[4:5], s[8:9], 12
	v_lshl_add_u64 v[60:61], v[40:41], 0, s[4:5]
	s_mov_b64 s[4:5], 0x200000
	global_load_dwordx4 v[104:107], v[60:61], off
	global_load_dwordx4 v[108:111], v[60:61], off offset:1024
	global_load_dwordx4 v[112:115], v[60:61], off offset:2048
	global_load_dwordx4 v[116:119], v[60:61], off offset:3072
	v_lshl_add_u64 v[60:61], v[60:61], 0, s[4:5]
	global_load_dwordx4 v[120:123], v[60:61], off
	global_load_dwordx4 v[124:127], v[60:61], off offset:1024
	global_load_dwordx4 v[128:131], v[60:61], off offset:2048
	global_load_dwordx4 v[132:135], v[60:61], off offset:3072
	v_lshl_add_u64 v[60:61], v[60:61], 0, s[4:5]
	global_load_dwordx4 v[136:139], v[60:61], off
	global_load_dwordx4 v[140:143], v[60:61], off offset:1024
	global_load_dwordx4 v[144:147], v[60:61], off offset:2048
	global_load_dwordx4 v[148:151], v[60:61], off offset:3072
	v_lshl_add_u64 v[60:61], v[60:61], 0, s[4:5]
	global_load_dwordx4 v[152:155], v[60:61], off
	global_load_dwordx4 v[156:159], v[60:61], off offset:1024
	global_load_dwordx4 v[160:163], v[60:61], off offset:2048
	global_load_dwordx4 v[164:167], v[60:61], off offset:3072
	v_lshl_add_u64 v[60:61], v[60:61], 0, s[4:5]
	global_load_dwordx4 v[168:171], v[60:61], off
	global_load_dwordx4 v[172:175], v[60:61], off offset:1024
	global_load_dwordx4 v[176:179], v[60:61], off offset:2048
	global_load_dwordx4 v[180:183], v[60:61], off offset:3072
	v_lshl_add_u64 v[60:61], v[60:61], 0, s[4:5]
	global_load_dwordx4 v[184:187], v[60:61], off
	global_load_dwordx4 v[188:191], v[60:61], off offset:1024
	global_load_dwordx4 v[192:195], v[60:61], off offset:2048
	global_load_dwordx4 v[196:199], v[60:61], off offset:3072
	v_lshl_add_u64 v[60:61], v[60:61], 0, s[4:5]
	global_load_dwordx4 v[200:203], v[60:61], off
	global_load_dwordx4 v[204:207], v[60:61], off offset:1024
	global_load_dwordx4 v[208:211], v[60:61], off offset:2048
	global_load_dwordx4 v[212:215], v[60:61], off offset:3072
	v_lshl_add_u64 v[60:61], v[60:61], 0, s[4:5]
	s_waitcnt vmcnt(0)
	v_pk_add_f32 v[104:105], v[104:105], v[120:121]
	v_pk_add_f32 v[106:107], v[106:107], v[122:123]
	v_pk_add_f32 v[136:137], v[136:137], v[152:153]
	v_pk_add_f32 v[138:139], v[138:139], v[154:155]
	v_pk_add_f32 v[168:169], v[168:169], v[184:185]
	v_pk_add_f32 v[170:171], v[170:171], v[186:187]
	v_pk_add_f32 v[168:169], v[168:169], v[200:201]
	v_pk_add_f32 v[170:171], v[170:171], v[202:203]
	v_pk_add_f32 v[104:105], v[104:105], v[136:137]
	v_pk_add_f32 v[106:107], v[106:107], v[138:139]
	v_pk_add_f32 v[104:105], v[104:105], v[168:169]
	v_pk_add_f32 v[106:107], v[106:107], v[170:171]
	v_pk_add_f32 v[20:21], v[20:21], v[104:105]
	v_pk_add_f32 v[22:23], v[22:23], v[106:107]
	v_pk_add_f32 v[108:109], v[108:109], v[124:125]
	v_pk_add_f32 v[110:111], v[110:111], v[126:127]
	v_pk_add_f32 v[140:141], v[140:141], v[156:157]
	v_pk_add_f32 v[142:143], v[142:143], v[158:159]
	v_pk_add_f32 v[172:173], v[172:173], v[188:189]
	v_pk_add_f32 v[174:175], v[174:175], v[190:191]
	v_pk_add_f32 v[172:173], v[172:173], v[204:205]
	v_pk_add_f32 v[174:175], v[174:175], v[206:207]
	v_pk_add_f32 v[108:109], v[108:109], v[140:141]
	v_pk_add_f32 v[110:111], v[110:111], v[142:143]
	v_pk_add_f32 v[108:109], v[108:109], v[172:173]
	v_pk_add_f32 v[110:111], v[110:111], v[174:175]
	v_pk_add_f32 v[24:25], v[24:25], v[108:109]
	v_pk_add_f32 v[26:27], v[26:27], v[110:111]
	v_pk_add_f32 v[112:113], v[112:113], v[128:129]
	v_pk_add_f32 v[114:115], v[114:115], v[130:131]
	v_pk_add_f32 v[144:145], v[144:145], v[160:161]
	v_pk_add_f32 v[146:147], v[146:147], v[162:163]
	v_pk_add_f32 v[176:177], v[176:177], v[192:193]
	v_pk_add_f32 v[178:179], v[178:179], v[194:195]
	v_pk_add_f32 v[176:177], v[176:177], v[208:209]
	v_pk_add_f32 v[178:179], v[178:179], v[210:211]
	v_pk_add_f32 v[112:113], v[112:113], v[144:145]
	v_pk_add_f32 v[114:115], v[114:115], v[146:147]
	v_pk_add_f32 v[112:113], v[112:113], v[176:177]
	v_pk_add_f32 v[114:115], v[114:115], v[178:179]
	v_pk_add_f32 v[16:17], v[16:17], v[112:113]
	v_pk_add_f32 v[18:19], v[18:19], v[114:115]
	v_pk_add_f32 v[116:117], v[116:117], v[132:133]
	v_pk_add_f32 v[118:119], v[118:119], v[134:135]
	v_pk_add_f32 v[148:149], v[148:149], v[164:165]
	v_pk_add_f32 v[150:151], v[150:151], v[166:167]
	v_pk_add_f32 v[180:181], v[180:181], v[196:197]
	v_pk_add_f32 v[182:183], v[182:183], v[198:199]
	v_pk_add_f32 v[180:181], v[180:181], v[212:213]
	v_pk_add_f32 v[182:183], v[182:183], v[214:215]
	v_pk_add_f32 v[116:117], v[116:117], v[148:149]
	v_pk_add_f32 v[118:119], v[118:119], v[150:151]
	v_pk_add_f32 v[116:117], v[116:117], v[180:181]
	v_pk_add_f32 v[118:119], v[118:119], v[182:183]
	v_pk_add_f32 v[28:29], v[28:29], v[116:117]
	v_pk_add_f32 v[30:31], v[30:31], v[118:119]
	global_load_dwordx4 v[104:107], v[60:61], off
	global_load_dwordx4 v[108:111], v[60:61], off offset:1024
	global_load_dwordx4 v[112:115], v[60:61], off offset:2048
	global_load_dwordx4 v[116:119], v[60:61], off offset:3072
	v_lshl_add_u64 v[60:61], v[60:61], 0, s[4:5]
	global_load_dwordx4 v[120:123], v[60:61], off
	global_load_dwordx4 v[124:127], v[60:61], off offset:1024
	global_load_dwordx4 v[128:131], v[60:61], off offset:2048
	global_load_dwordx4 v[132:135], v[60:61], off offset:3072
	v_lshl_add_u64 v[60:61], v[60:61], 0, s[4:5]
	global_load_dwordx4 v[136:139], v[60:61], off
	global_load_dwordx4 v[140:143], v[60:61], off offset:1024
	global_load_dwordx4 v[144:147], v[60:61], off offset:2048
	global_load_dwordx4 v[148:151], v[60:61], off offset:3072
	v_lshl_add_u64 v[60:61], v[60:61], 0, s[4:5]
	global_load_dwordx4 v[152:155], v[60:61], off
	global_load_dwordx4 v[156:159], v[60:61], off offset:1024
	global_load_dwordx4 v[160:163], v[60:61], off offset:2048
	global_load_dwordx4 v[164:167], v[60:61], off offset:3072
	v_lshl_add_u64 v[60:61], v[60:61], 0, s[4:5]
	global_load_dwordx4 v[168:171], v[60:61], off
	global_load_dwordx4 v[172:175], v[60:61], off offset:1024
	global_load_dwordx4 v[176:179], v[60:61], off offset:2048
	global_load_dwordx4 v[180:183], v[60:61], off offset:3072
	v_lshl_add_u64 v[60:61], v[60:61], 0, s[4:5]
	global_load_dwordx4 v[184:187], v[60:61], off
	global_load_dwordx4 v[188:191], v[60:61], off offset:1024
	global_load_dwordx4 v[192:195], v[60:61], off offset:2048
	global_load_dwordx4 v[196:199], v[60:61], off offset:3072
	v_lshl_add_u64 v[60:61], v[60:61], 0, s[4:5]
	global_load_dwordx4 v[200:203], v[60:61], off
	global_load_dwordx4 v[204:207], v[60:61], off offset:1024
	global_load_dwordx4 v[208:211], v[60:61], off offset:2048
	global_load_dwordx4 v[212:215], v[60:61], off offset:3072
	v_lshl_add_u64 v[60:61], v[60:61], 0, s[4:5]
	s_waitcnt vmcnt(0)
; template <bool FINAL>
; DI void norm_rows(const Params& p, const float* gain, int in_mode  , int npart  , int pool_j  , int gw, int NGW, int lane) {
;     ...
;             for (; k + 4 <= npart; k += 4) {
;                 f32x4 t[4][4];
; #pragma unroll
;                 for (int kk = 0; kk < 4; ++kk)
; #pragma unroll
;                     for (int j = 0; j < 4; ++j) t[kk][j] = *(const f32x4*)(pp + (size_t)(k + kk) * MS * D + 256 * j);
; #pragma unroll
;                 for (int j = 0; j < 4; ++j) v[j] += (t[0][j] + t[1][j]) + (t[2][j] + t[3][j]);
;             }
	v_pk_add_f32 v[104:105], v[104:105], v[120:121]
	v_pk_add_f32 v[106:107], v[106:107], v[122:123]
	v_pk_add_f32 v[136:137], v[136:137], v[152:153]
	v_pk_add_f32 v[138:139], v[138:139], v[154:155]
	v_pk_add_f32 v[168:169], v[168:169], v[184:185]
	v_pk_add_f32 v[170:171], v[170:171], v[186:187]
	v_pk_add_f32 v[168:169], v[168:169], v[200:201]
	v_pk_add_f32 v[170:171], v[170:171], v[202:203]
	v_pk_add_f32 v[104:105], v[104:105], v[136:137]
	v_pk_add_f32 v[106:107], v[106:107], v[138:139]
	v_pk_add_f32 v[104:105], v[104:105], v[168:169]
	v_pk_add_f32 v[106:107], v[106:107], v[170:171]
	v_pk_add_f32 v[20:21], v[20:21], v[104:105]
	v_pk_add_f32 v[22:23], v[22:23], v[106:107]
	v_pk_add_f32 v[108:109], v[108:109], v[124:125]
	v_pk_add_f32 v[110:111], v[110:111], v[126:127]
	v_pk_add_f32 v[140:141], v[140:141], v[156:157]
	v_pk_add_f32 v[142:143], v[142:143], v[158:159]
	v_pk_add_f32 v[172:173], v[172:173], v[188:189]
	v_pk_add_f32 v[174:175], v[174:175], v[190:191]
	v_pk_add_f32 v[172:173], v[172:173], v[204:205]
	v_pk_add_f32 v[174:175], v[174:175], v[206:207]
	v_pk_add_f32 v[108:109], v[108:109], v[140:141]
	v_pk_add_f32 v[110:111], v[110:111], v[142:143]
	v_pk_add_f32 v[108:109], v[108:109], v[172:173]
	v_pk_add_f32 v[110:111], v[110:111], v[174:175]
	v_pk_add_f32 v[24:25], v[24:25], v[108:109]
	v_pk_add_f32 v[26:27], v[26:27], v[110:111]
	v_pk_add_f32 v[112:113], v[112:113], v[128:129]
	v_pk_add_f32 v[114:115], v[114:115], v[130:131]
	v_pk_add_f32 v[144:145], v[144:145], v[160:161]
	v_pk_add_f32 v[146:147], v[146:147], v[162:163]
	v_pk_add_f32 v[176:177], v[176:177], v[192:193]
	v_pk_add_f32 v[178:179], v[178:179], v[194:195]
	v_pk_add_f32 v[176:177], v[176:177], v[208:209]
	v_pk_add_f32 v[178:179], v[178:179], v[210:211]
	v_pk_add_f32 v[112:113], v[112:113], v[144:145]
	v_pk_add_f32 v[114:115], v[114:115], v[146:147]
	v_pk_add_f32 v[112:113], v[112:113], v[176:177]
	v_pk_add_f32 v[114:115], v[114:115], v[178:179]
	v_pk_add_f32 v[16:17], v[16:17], v[112:113]
	v_pk_add_f32 v[18:19], v[18:19], v[114:115]
	v_pk_add_f32 v[116:117], v[116:117], v[132:133]
	v_pk_add_f32 v[118:119], v[118:119], v[134:135]
	v_pk_add_f32 v[148:149], v[148:149], v[164:165]
	v_pk_add_f32 v[150:151], v[150:151], v[166:167]
	v_pk_add_f32 v[180:181], v[180:181], v[196:197]
	v_pk_add_f32 v[182:183], v[182:183], v[198:199]
	v_pk_add_f32 v[180:181], v[180:181], v[212:213]
	v_pk_add_f32 v[182:183], v[182:183], v[214:215]
	v_pk_add_f32 v[116:117], v[116:117], v[148:149]
	v_pk_add_f32 v[118:119], v[118:119], v[150:151]
	v_pk_add_f32 v[116:117], v[116:117], v[180:181]
	v_pk_add_f32 v[118:119], v[118:119], v[182:183]
	v_pk_add_f32 v[28:29], v[28:29], v[116:117]
	v_pk_add_f32 v[30:31], v[30:31], v[118:119]
	global_load_dwordx4 v[104:107], v[60:61], off
	global_load_dwordx4 v[108:111], v[60:61], off offset:1024
	global_load_dwordx4 v[112:115], v[60:61], off offset:2048
	global_load_dwordx4 v[116:119], v[60:61], off offset:3072
	v_lshl_add_u64 v[60:61], v[60:61], 0, s[4:5]
	global_load_dwordx4 v[120:123], v[60:61], off
	global_load_dwordx4 v[124:127], v[60:61], off offset:1024
	global_load_dwordx4 v[128:131], v[60:61], off offset:2048
	global_load_dwordx4 v[132:135], v[60:61], off offset:3072
	v_lshl_add_u64 v[60:61], v[60:61], 0, s[4:5]
	global_load_dwordx4 v[136:139], v[60:61], off
	global_load_dwordx4 v[140:143], v[60:61], off offset:1024
	global_load_dwordx4 v[144:147], v[60:61], off offset:2048
	global_load_dwordx4 v[148:151], v[60:61], off offset:3072
	v_lshl_add_u64 v[60:61], v[60:61], 0, s[4:5]
	global_load_dwordx4 v[152:155], v[60:61], off
	global_load_dwordx4 v[156:159], v[60:61], off offset:1024
	global_load_dwordx4 v[160:163], v[60:61], off offset:2048
	global_load_dwordx4 v[164:167], v[60:61], off offset:3072
	v_lshl_add_u64 v[60:61], v[60:61], 0, s[4:5]
	global_load_dwordx4 v[168:171], v[60:61], off
	global_load_dwordx4 v[172:175], v[60:61], off offset:1024
	global_load_dwordx4 v[176:179], v[60:61], off offset:2048
	global_load_dwordx4 v[180:183], v[60:61], off offset:3072
	v_lshl_add_u64 v[60:61], v[60:61], 0, s[4:5]
	global_load_dwordx4 v[184:187], v[60:61], off
	global_load_dwordx4 v[188:191], v[60:61], off offset:1024
	global_load_dwordx4 v[192:195], v[60:61], off offset:2048
	global_load_dwordx4 v[196:199], v[60:61], off offset:3072
	v_lshl_add_u64 v[60:61], v[60:61], 0, s[4:5]
	global_load_dwordx4 v[200:203], v[60:61], off
	global_load_dwordx4 v[204:207], v[60:61], off offset:1024
	global_load_dwordx4 v[208:211], v[60:61], off offset:2048
	global_load_dwordx4 v[212:215], v[60:61], off offset:3072
	v_lshl_add_u64 v[60:61], v[60:61], 0, s[4:5]
	s_waitcnt vmcnt(0)
; template <bool FINAL>
; DI void norm_rows(const Params& p, const float* gain, int in_mode  , int npart  , int pool_j  , int gw, int NGW, int lane) {
;     ...
;             for (; k + 4 <= npart; k += 4) {
;                 f32x4 t[4][4];
; #pragma unroll
;                 for (int kk = 0; kk < 4; ++kk)
; #pragma unroll
;                     for (int j = 0; j < 4; ++j) t[kk][j] = *(const f32x4*)(pp + (size_t)(k + kk) * MS * D + 256 * j);
; #pragma unroll
;                 for (int j = 0; j < 4; ++j) v[j] += (t[0][j] + t[1][j]) + (t[2][j] + t[3][j]);
;             }
;             for (; k + 2 <= npart; k += 2) {
;                 f32x4 t[2][4];
; #pragma unroll
;                 for (int kk = 0; kk < 2; ++kk)
; #pragma unroll
;                     for (int j = 0; j < 4; ++j) t[kk][j] = *(const f32x4*)(pp + (size_t)(k + kk) * MS * D + 256 * j);
; #pragma unroll
;                 for (int j = 0; j < 4; ++j) v[j] += t[0][j] + t[1][j];
;             }
;             if (!FINAL) {
; #pragma unroll
;                 for (int j = 0; j < 4; ++j) *(f32x4*)(X + (size_t)row * D + 4 * lane + 256 * j) = v[j]; }
	v_pk_add_f32 v[104:105], v[104:105], v[120:121]
	v_pk_add_f32 v[106:107], v[106:107], v[122:123]
	v_pk_add_f32 v[136:137], v[136:137], v[152:153]
	v_pk_add_f32 v[138:139], v[138:139], v[154:155]
	v_pk_add_f32 v[168:169], v[168:169], v[184:185]
	v_pk_add_f32 v[170:171], v[170:171], v[186:187]
	v_pk_add_f32 v[168:169], v[168:169], v[200:201]
	v_pk_add_f32 v[170:171], v[170:171], v[202:203]
	v_pk_add_f32 v[104:105], v[104:105], v[136:137]
	v_pk_add_f32 v[106:107], v[106:107], v[138:139]
	v_pk_add_f32 v[104:105], v[104:105], v[168:169]
	v_pk_add_f32 v[106:107], v[106:107], v[170:171]
	v_pk_add_f32 v[20:21], v[20:21], v[104:105]
	v_pk_add_f32 v[22:23], v[22:23], v[106:107]
	v_pk_add_f32 v[108:109], v[108:109], v[124:125]
	v_pk_add_f32 v[110:111], v[110:111], v[126:127]
	v_pk_add_f32 v[140:141], v[140:141], v[156:157]
	v_pk_add_f32 v[142:143], v[142:143], v[158:159]
	v_pk_add_f32 v[172:173], v[172:173], v[188:189]
	v_pk_add_f32 v[174:175], v[174:175], v[190:191]
	v_pk_add_f32 v[172:173], v[172:173], v[204:205]
	v_pk_add_f32 v[174:175], v[174:175], v[206:207]
	v_pk_add_f32 v[108:109], v[108:109], v[140:141]
	v_pk_add_f32 v[110:111], v[110:111], v[142:143]
	v_pk_add_f32 v[108:109], v[108:109], v[172:173]
	v_pk_add_f32 v[110:111], v[110:111], v[174:175]
	v_pk_add_f32 v[24:25], v[24:25], v[108:109]
	v_pk_add_f32 v[26:27], v[26:27], v[110:111]
	v_pk_add_f32 v[112:113], v[112:113], v[128:129]
	v_pk_add_f32 v[114:115], v[114:115], v[130:131]
	v_pk_add_f32 v[144:145], v[144:145], v[160:161]
	v_pk_add_f32 v[146:147], v[146:147], v[162:163]
	v_pk_add_f32 v[176:177], v[176:177], v[192:193]
	v_pk_add_f32 v[178:179], v[178:179], v[194:195]
	v_pk_add_f32 v[176:177], v[176:177], v[208:209]
	v_pk_add_f32 v[178:179], v[178:179], v[210:211]
	v_pk_add_f32 v[112:113], v[112:113], v[144:145]
	v_pk_add_f32 v[114:115], v[114:115], v[146:147]
	v_pk_add_f32 v[112:113], v[112:113], v[176:177]
	v_pk_add_f32 v[114:115], v[114:115], v[178:179]
	v_pk_add_f32 v[16:17], v[16:17], v[112:113]
	v_pk_add_f32 v[18:19], v[18:19], v[114:115]
	v_pk_add_f32 v[116:117], v[116:117], v[132:133]
	v_pk_add_f32 v[118:119], v[118:119], v[134:135]
	v_pk_add_f32 v[148:149], v[148:149], v[164:165]
	v_pk_add_f32 v[150:151], v[150:151], v[166:167]
	v_pk_add_f32 v[180:181], v[180:181], v[196:197]
	v_pk_add_f32 v[182:183], v[182:183], v[198:199]
	v_pk_add_f32 v[180:181], v[180:181], v[212:213]
	v_pk_add_f32 v[182:183], v[182:183], v[214:215]
	v_pk_add_f32 v[116:117], v[116:117], v[148:149]
	v_pk_add_f32 v[118:119], v[118:119], v[150:151]
	v_pk_add_f32 v[116:117], v[116:117], v[180:181]
	v_pk_add_f32 v[118:119], v[118:119], v[182:183]
	v_pk_add_f32 v[28:29], v[28:29], v[116:117]
	v_pk_add_f32 v[30:31], v[30:31], v[118:119]
	global_load_dwordx4 v[104:107], v[60:61], off
	global_load_dwordx4 v[108:111], v[60:61], off offset:1024
	global_load_dwordx4 v[112:115], v[60:61], off offset:2048
	global_load_dwordx4 v[116:119], v[60:61], off offset:3072
	v_lshl_add_u64 v[60:61], v[60:61], 0, s[4:5]
	s_waitcnt vmcnt(0)
	v_pk_add_f32 v[20:21], v[20:21], v[104:105]
	v_pk_add_f32 v[22:23], v[22:23], v[106:107]
	v_pk_add_f32 v[24:25], v[24:25], v[108:109]
	v_pk_add_f32 v[26:27], v[26:27], v[110:111]
	v_pk_add_f32 v[16:17], v[16:17], v[112:113]
	v_pk_add_f32 v[18:19], v[18:19], v[114:115]
	v_pk_add_f32 v[28:29], v[28:29], v[116:117]
	v_pk_add_f32 v[30:31], v[30:31], v[118:119]
	s_mov_b32 s8, s28
	s_lshl_b64 s[4:5], s[8:9], 12
	v_lshl_add_u64 v[32:33], v[38:39], 0, s[4:5]
	global_store_dwordx4 v[32:33], v[20:23], off
	global_store_dwordx4 v[32:33], v[24:27], off offset:1024
	global_store_dwordx4 v[32:33], v[16:19], off offset:2048
	global_store_dwordx4 v[32:33], v[28:31], off offset:3072
	v_mov_b32_e32 v48, v27
	v_mov_b32_e32 v49, v25
	v_mov_b32_e32 v32, v31
	v_mov_b32_e32 v44, v26
	v_mov_b32_e32 v45, v24
	v_mov_b32_e32 v46, v23
	v_mov_b32_e32 v47, v21
	v_mov_b32_e32 v34, v22
	v_mov_b32_e32 v35, v20
